# EpiRes epilogue v2: in-wave LDS transpose -> full-line coalesced src loads and write-through (sc1) stores, 14-deep load ring
# speedup vs baseline: 1.0194x; 1.0194x over previous
;     __device__ __forceinline__ void operator()(const f32x4 (&acc)[2][2][4][2], const Unit& u, int wr, int wc, int fr, int fq) const {
;         const float* src; float* dst; int b;
;         if (u.pm < 128) { src = src_lat + (size_t)u.pm * BM * 1024; dst = dst_lat + (size_t)u.pm * BM * 1024; b = u.pm >> 5; }
;         else { src = src_ctx + (size_t)(u.pm - 128) * BM * 1024; dst = dst_ctx + (size_t)(u.pm - 128) * BM * 1024; b = 4; }
;         const float* g = gate + b * 6144;
;         const int col0 = u.pn * BM + wc * 32 + 4 * fq;
; #pragma unroll
;         for (int bj = 0; bj < 2; ++bj)
; #pragma unroll
;             for (int n = 0; n < 2; ++n) { const f32x4 gv = *(const f32x4*)(g + col0 + bj * HALF + n * 16);
; #pragma unroll
;                 for (int ai = 0; ai < 2; ++ai)
; #pragma unroll
;                     for (int m = 0; m < 4; ++m) { const size_t off = (size_t)(ai * HALF + wr * 64 + m * 16 + fr) * 1024 + col0 + bj * HALF + n * 16;
;                         const f32x4 s = *(const f32x4*)(src + off); *(f32x4*)(dst + off) = s + gv * acc[ai][bj][m][n]; } }
.LBB0_549:
	s_lshl_b64 s[14:15], s[20:21], 2
	s_add_u32 s14, s35, s14
	s_addc_u32 s15, s36, s15
	s_add_u32 s20, s18, 0x80000
	s_addc_u32 s21, s19, 0
	s_add_u32 s22, s16, 0x80000
	s_addc_u32 s23, s17, 0
	v_mbcnt_lo_u32_b32 v186, -1, 0
	v_mbcnt_hi_u32_b32 v186, -1, v186
	v_lshrrev_b32_e32 v187, 10, v142
	v_and_b32_e32 v187, 64, v187
	v_and_b32_e32 v188, 0x60, v169
	v_mul_u32_u24_e32 v189, 0xc0, v187
	v_mul_u32_u24_e32 v192, 0x60, v188
	v_add_u32_e32 v189, v189, v192
	v_add_u32_e32 v189, 0x20000, v189
	v_and_b32_e32 v192, 15, v186
	v_lshrrev_b32_e32 v193, 4, v186
	v_mul_u32_u24_e32 v192, 0x90, v192
	v_lshl_add_u32 v192, v193, 4, v192
	v_add_u32_e32 v38, v189, v192
	v_lshrrev_b32_e32 v190, 3, v186
	v_and_b32_e32 v191, 7, v186
	v_mul_u32_u24_e32 v192, 0x90, v190
	v_lshl_add_u32 v192, v191, 4, v192
	v_add_u32_e32 v250, v189, v192
	v_add_u32_e32 v193, v187, v190
	v_lshlrev_b32_e32 v193, 12, v193
	v_lshl_or_b32 v193, v188, 2, v193
	v_lshl_or_b32 v193, v191, 4, v193
	v_lshl_or_b32 v166, s40, 10, v193
	v_and_b32_e32 v251, 0xfff, v166
	v_add_u32_e32 v167, 0x8000, v166
	v_add_u32_e32 v180, 0x10000, v166
	v_add_u32_e32 v181, 0x18000, v166
	v_add_u32_e32 v202, 0x20000, v166
	v_add_u32_e32 v203, 0x28000, v166
	v_add_u32_e32 v212, 0x30000, v166
	v_add_u32_e32 v213, 0x38000, v166
	global_load_dwordx4 v[138:141], v251, s[14:15]
	global_load_dwordx4 v[162:165], v251, s[14:15] offset:512
	global_load_dwordx4 v[172:175], v166, s[18:19]
	global_load_dwordx4 v[176:179], v166, s[18:19] offset:512
	global_load_dwordx4 v[186:189], v167, s[18:19]
	global_load_dwordx4 v[190:193], v167, s[18:19] offset:512
	global_load_dwordx4 v[194:197], v180, s[18:19]
	global_load_dwordx4 v[198:201], v180, s[18:19] offset:512
	global_load_dwordx4 v[208:211], v181, s[18:19]
	global_load_dwordx4 v[218:221], v181, s[18:19] offset:512
	global_load_dwordx4 v[226:229], v202, s[18:19]
	global_load_dwordx4 v[230:233], v202, s[18:19] offset:512
	global_load_dwordx4 v[234:237], v203, s[18:19]
	global_load_dwordx4 v[238:241], v203, s[18:19] offset:512
	global_load_dwordx4 v[242:245], v212, s[18:19]
	global_load_dwordx4 v[246:249], v212, s[18:19] offset:512
	ds_write_b128 v38, v[134:137]
	ds_write_b128 v38, v[106:109] offset:64
	ds_read_b128 v[134:137], v250
	ds_read_b128 v[106:109], v250 offset:1152
	ds_write_b128 v38, v[82:85]
	ds_write_b128 v38, v[54:57] offset:64
	ds_read_b128 v[82:85], v250
	ds_read_b128 v[54:57], v250 offset:1152
	ds_write_b128 v38, v[130:133]
	ds_write_b128 v38, v[102:105] offset:64
	ds_read_b128 v[130:133], v250
	ds_read_b128 v[102:105], v250 offset:1152
	ds_write_b128 v38, v[74:77]
	ds_write_b128 v38, v[46:49] offset:64
	ds_read_b128 v[74:77], v250
	ds_read_b128 v[46:49], v250 offset:1152
	ds_write_b128 v38, v[126:129]
	ds_write_b128 v38, v[98:101] offset:64
	ds_read_b128 v[126:129], v250
	ds_read_b128 v[98:101], v250 offset:1152
	ds_write_b128 v38, v[66:69]
	ds_write_b128 v38, v[30:33] offset:64
	ds_read_b128 v[66:69], v250
	ds_read_b128 v[30:33], v250 offset:1152
	ds_write_b128 v38, v[122:125]
	ds_write_b128 v38, v[90:93] offset:64
	ds_read_b128 v[122:125], v250
	ds_read_b128 v[90:93], v250 offset:1152
	ds_write_b128 v38, v[58:61]
	ds_write_b128 v38, v[22:25] offset:64
	ds_read_b128 v[58:61], v250
	ds_read_b128 v[22:25], v250 offset:1152
	ds_write_b128 v38, v[118:121]
	ds_write_b128 v38, v[86:89] offset:64
	ds_read_b128 v[118:121], v250
	ds_read_b128 v[86:89], v250 offset:1152
	ds_write_b128 v38, v[50:53]
	ds_write_b128 v38, v[14:17] offset:64
	ds_read_b128 v[50:53], v250
	ds_read_b128 v[14:17], v250 offset:1152
	ds_write_b128 v38, v[114:117]
	ds_write_b128 v38, v[78:81] offset:64
	ds_read_b128 v[114:117], v250
	ds_read_b128 v[78:81], v250 offset:1152
	ds_write_b128 v38, v[42:45]
	ds_write_b128 v38, v[10:13] offset:64
	ds_read_b128 v[42:45], v250
	ds_read_b128 v[10:13], v250 offset:1152
	ds_write_b128 v38, v[110:113]
	ds_write_b128 v38, v[70:73] offset:64
	ds_read_b128 v[110:113], v250
	ds_read_b128 v[70:73], v250 offset:1152
	ds_write_b128 v38, v[26:29]
	ds_write_b128 v38, v[6:9] offset:64
	ds_read_b128 v[26:29], v250
	ds_read_b128 v[6:9], v250 offset:1152
	ds_write_b128 v38, v[94:97]
	ds_write_b128 v38, v[62:65] offset:64
	ds_read_b128 v[94:97], v250
	ds_read_b128 v[62:65], v250 offset:1152
	ds_write_b128 v38, v[18:21]
	ds_write_b128 v38, v[2:5] offset:64
	ds_read_b128 v[18:21], v250
	ds_read_b128 v[2:5], v250 offset:1152
	s_waitcnt lgkmcnt(0)
	s_waitcnt vmcnt(13)
	v_pk_fma_f32 v[134:135], v[134:135], v[138:139], v[172:173]
	v_pk_fma_f32 v[136:137], v[136:137], v[140:141], v[174:175]
	global_store_dwordx4 v166, v[134:137], s[16:17] sc1
	global_load_dwordx4 v[172:175], v213, s[18:19]
	s_waitcnt vmcnt(14)
	v_pk_fma_f32 v[82:83], v[82:83], v[162:163], v[176:177]
	v_pk_fma_f32 v[84:85], v[84:85], v[164:165], v[178:179]
	global_store_dwordx4 v166, v[82:85], s[16:17] offset:512 sc1
	global_load_dwordx4 v[176:179], v213, s[18:19] offset:512
	s_waitcnt vmcnt(15)
	v_pk_fma_f32 v[106:107], v[106:107], v[138:139], v[186:187]
	v_pk_fma_f32 v[108:109], v[108:109], v[140:141], v[188:189]
	global_store_dwordx4 v167, v[106:109], s[16:17] sc1
	global_load_dwordx4 v[186:189], v166, s[20:21]
	s_waitcnt vmcnt(16)
	v_pk_fma_f32 v[54:55], v[54:55], v[162:163], v[190:191]
	v_pk_fma_f32 v[56:57], v[56:57], v[164:165], v[192:193]
	global_store_dwordx4 v167, v[54:57], s[16:17] offset:512 sc1
	global_load_dwordx4 v[190:193], v166, s[20:21] offset:512
	s_waitcnt vmcnt(17)
	v_pk_fma_f32 v[130:131], v[130:131], v[138:139], v[194:195]
	v_pk_fma_f32 v[132:133], v[132:133], v[140:141], v[196:197]
	global_store_dwordx4 v180, v[130:133], s[16:17] sc1
	global_load_dwordx4 v[194:197], v167, s[20:21]
	s_waitcnt vmcnt(18)
; #define PG8_BAR __builtin_amdgcn_s_barrier()
;     __device__ __forceinline__ void operator()(const f32x4 (&acc)[2][2][4][2], const Unit& u, int wr, int wc, int fr, int fq) const {
;     ...
;             for (int n = 0; n < 2; ++n) { const f32x4 gv = *(const f32x4*)(g + col0 + bj * HALF + n * 16);
; #pragma unroll
;                 for (int ai = 0; ai < 2; ++ai)
; #pragma unroll
;                     for (int m = 0; m < 4; ++m) { const size_t off = (size_t)(ai * HALF + wr * 64 + m * 16 + fr) * 1024 + col0 + bj * HALF + n * 16;
;                         const f32x4 s = *(const f32x4*)(src + off); *(f32x4*)(dst + off) = s + gv * acc[ai][bj][m][n]; } }
; template <class Epi, class Sched, bool ALIGN_EPI = false, bool SP2 = false>
; __device__ __forceinline__ void gemm_phase(PG8_LAS unsigned char* lds, const Gemm g, const Sched& S, const Epi& E) {
;     ...
;         if (!has_next) break;
; #pragma unroll
;         for (int a = 0; a < 2; ++a)
; #pragma unroll
;             for (int b = 0; b < 2; ++b)
; #pragma unroll
;                 for (int m = 0; m < 4; ++m)
; #pragma unroll
;                     for (int n = 0; n < 2; ++n) acc[a][b][m][n] = (f32x4){0.f, 0.f, 0.f, 0.f};
;         cur = nxt; cA = nA; cB = nB; ++ui;
;         if constexpr (ALIGN_EPI) { if (wr == 1) PG8_BAR; }
	v_pk_fma_f32 v[74:75], v[74:75], v[162:163], v[198:199]
	v_pk_fma_f32 v[76:77], v[76:77], v[164:165], v[200:201]
	global_store_dwordx4 v180, v[74:77], s[16:17] offset:512 sc1
	global_load_dwordx4 v[198:201], v167, s[20:21] offset:512
	s_waitcnt vmcnt(19)
	v_pk_fma_f32 v[102:103], v[102:103], v[138:139], v[208:209]
	v_pk_fma_f32 v[104:105], v[104:105], v[140:141], v[210:211]
	global_store_dwordx4 v181, v[102:105], s[16:17] sc1
	global_load_dwordx4 v[208:211], v180, s[20:21]
	s_waitcnt vmcnt(20)
	v_pk_fma_f32 v[46:47], v[46:47], v[162:163], v[218:219]
	v_pk_fma_f32 v[48:49], v[48:49], v[164:165], v[220:221]
	global_store_dwordx4 v181, v[46:49], s[16:17] offset:512 sc1
	global_load_dwordx4 v[218:221], v180, s[20:21] offset:512
	s_waitcnt vmcnt(21)
	v_pk_fma_f32 v[126:127], v[126:127], v[138:139], v[226:227]
	v_pk_fma_f32 v[128:129], v[128:129], v[140:141], v[228:229]
	global_store_dwordx4 v202, v[126:129], s[16:17] sc1
	global_load_dwordx4 v[226:229], v181, s[20:21]
	s_waitcnt vmcnt(22)
	v_pk_fma_f32 v[66:67], v[66:67], v[162:163], v[230:231]
	v_pk_fma_f32 v[68:69], v[68:69], v[164:165], v[232:233]
	global_store_dwordx4 v202, v[66:69], s[16:17] offset:512 sc1
	global_load_dwordx4 v[230:233], v181, s[20:21] offset:512
	s_waitcnt vmcnt(23)
	v_pk_fma_f32 v[98:99], v[98:99], v[138:139], v[234:235]
	v_pk_fma_f32 v[100:101], v[100:101], v[140:141], v[236:237]
	global_store_dwordx4 v203, v[98:101], s[16:17] sc1
	global_load_dwordx4 v[234:237], v202, s[20:21]
	s_waitcnt vmcnt(24)
	v_pk_fma_f32 v[30:31], v[30:31], v[162:163], v[238:239]
	v_pk_fma_f32 v[32:33], v[32:33], v[164:165], v[240:241]
	global_store_dwordx4 v203, v[30:33], s[16:17] offset:512 sc1
	global_load_dwordx4 v[238:241], v202, s[20:21] offset:512
	s_waitcnt vmcnt(25)
	v_pk_fma_f32 v[122:123], v[122:123], v[138:139], v[242:243]
	v_pk_fma_f32 v[124:125], v[124:125], v[140:141], v[244:245]
	global_store_dwordx4 v212, v[122:125], s[16:17] sc1
	global_load_dwordx4 v[242:245], v203, s[20:21]
	s_waitcnt vmcnt(26)
	v_pk_fma_f32 v[58:59], v[58:59], v[162:163], v[246:247]
	v_pk_fma_f32 v[60:61], v[60:61], v[164:165], v[248:249]
	global_store_dwordx4 v212, v[58:61], s[16:17] offset:512 sc1
	global_load_dwordx4 v[246:249], v203, s[20:21] offset:512
	s_waitcnt vmcnt(26)
	v_pk_fma_f32 v[90:91], v[90:91], v[138:139], v[172:173]
	v_pk_fma_f32 v[92:93], v[92:93], v[140:141], v[174:175]
	global_store_dwordx4 v213, v[90:93], s[16:17] sc1
	global_load_dwordx4 v[172:175], v212, s[20:21]
	s_waitcnt vmcnt(26)
	v_pk_fma_f32 v[22:23], v[22:23], v[162:163], v[176:177]
	v_pk_fma_f32 v[24:25], v[24:25], v[164:165], v[178:179]
	global_store_dwordx4 v213, v[22:25], s[16:17] offset:512 sc1
	global_load_dwordx4 v[176:179], v212, s[20:21] offset:512
	s_waitcnt vmcnt(26)
	v_pk_fma_f32 v[118:119], v[118:119], v[138:139], v[186:187]
	v_pk_fma_f32 v[120:121], v[120:121], v[140:141], v[188:189]
	global_store_dwordx4 v166, v[118:121], s[22:23] sc1
	global_load_dwordx4 v[186:189], v213, s[20:21]
	s_waitcnt vmcnt(26)
	v_pk_fma_f32 v[50:51], v[50:51], v[162:163], v[190:191]
	v_pk_fma_f32 v[52:53], v[52:53], v[164:165], v[192:193]
	global_store_dwordx4 v166, v[50:53], s[22:23] offset:512 sc1
	global_load_dwordx4 v[190:193], v213, s[20:21] offset:512
	s_waitcnt vmcnt(26)
	v_pk_fma_f32 v[86:87], v[86:87], v[138:139], v[194:195]
	v_pk_fma_f32 v[88:89], v[88:89], v[140:141], v[196:197]
	global_store_dwordx4 v167, v[86:89], s[22:23] sc1
	s_waitcnt vmcnt(25)
	v_pk_fma_f32 v[14:15], v[14:15], v[162:163], v[198:199]
	v_pk_fma_f32 v[16:17], v[16:17], v[164:165], v[200:201]
	global_store_dwordx4 v167, v[14:17], s[22:23] offset:512 sc1
	s_waitcnt vmcnt(24)
	v_pk_fma_f32 v[114:115], v[114:115], v[138:139], v[208:209]
	v_pk_fma_f32 v[116:117], v[116:117], v[140:141], v[210:211]
	global_store_dwordx4 v180, v[114:117], s[22:23] sc1
	s_waitcnt vmcnt(23)
	v_pk_fma_f32 v[42:43], v[42:43], v[162:163], v[218:219]
	v_pk_fma_f32 v[44:45], v[44:45], v[164:165], v[220:221]
	global_store_dwordx4 v180, v[42:45], s[22:23] offset:512 sc1
	s_waitcnt vmcnt(22)
	v_pk_fma_f32 v[78:79], v[78:79], v[138:139], v[226:227]
	v_pk_fma_f32 v[80:81], v[80:81], v[140:141], v[228:229]
	global_store_dwordx4 v181, v[78:81], s[22:23] sc1
	s_waitcnt vmcnt(21)
	v_pk_fma_f32 v[10:11], v[10:11], v[162:163], v[230:231]
	v_pk_fma_f32 v[12:13], v[12:13], v[164:165], v[232:233]
	global_store_dwordx4 v181, v[10:13], s[22:23] offset:512 sc1
	s_waitcnt vmcnt(20)
	v_pk_fma_f32 v[110:111], v[110:111], v[138:139], v[234:235]
	v_pk_fma_f32 v[112:113], v[112:113], v[140:141], v[236:237]
	global_store_dwordx4 v202, v[110:113], s[22:23] sc1
	s_waitcnt vmcnt(19)
	v_pk_fma_f32 v[26:27], v[26:27], v[162:163], v[238:239]
	v_pk_fma_f32 v[28:29], v[28:29], v[164:165], v[240:241]
	global_store_dwordx4 v202, v[26:29], s[22:23] offset:512 sc1
	s_waitcnt vmcnt(18)
	v_pk_fma_f32 v[70:71], v[70:71], v[138:139], v[242:243]
	v_pk_fma_f32 v[72:73], v[72:73], v[140:141], v[244:245]
	global_store_dwordx4 v203, v[70:73], s[22:23] sc1
	s_waitcnt vmcnt(17)
	v_pk_fma_f32 v[6:7], v[6:7], v[162:163], v[246:247]
	v_pk_fma_f32 v[8:9], v[8:9], v[164:165], v[248:249]
	global_store_dwordx4 v203, v[6:9], s[22:23] offset:512 sc1
	s_waitcnt vmcnt(16)
	v_pk_fma_f32 v[94:95], v[94:95], v[138:139], v[172:173]
	v_pk_fma_f32 v[96:97], v[96:97], v[140:141], v[174:175]
	global_store_dwordx4 v212, v[94:97], s[22:23] sc1
	s_waitcnt vmcnt(15)
	v_pk_fma_f32 v[18:19], v[18:19], v[162:163], v[176:177]
	v_pk_fma_f32 v[20:21], v[20:21], v[164:165], v[178:179]
	global_store_dwordx4 v212, v[18:21], s[22:23] offset:512 sc1
	s_waitcnt vmcnt(14)
	v_pk_fma_f32 v[62:63], v[62:63], v[138:139], v[186:187]
	v_pk_fma_f32 v[64:65], v[64:65], v[140:141], v[188:189]
	global_store_dwordx4 v213, v[62:65], s[22:23] sc1
	s_waitcnt vmcnt(13)
	v_pk_fma_f32 v[2:3], v[2:3], v[162:163], v[190:191]
	v_pk_fma_f32 v[4:5], v[4:5], v[164:165], v[192:193]
	global_store_dwordx4 v213, v[2:5], s[22:23] offset:512 sc1
	s_mov_b64 s[14:15], -1
	s_andn2_b64 vcc, exec, s[4:5]
	s_cbranch_vccnz .LBB0_534
	s_andn2_b64 vcc, exec, s[0:1]
	s_cbranch_vccnz .LBB0_533
	s_barrier
	s_branch .LBB0_533

;     __device__ __forceinline__ void operator()(const f32x4 (&acc)[2][2][4][2], const Unit& u, int wr, int wc, int fr, int fq) const {
;         const float* src; float* dst; int b;
;         if (u.pm < 128) { src = src_lat + (size_t)u.pm * BM * 1024; dst = dst_lat + (size_t)u.pm * BM * 1024; b = u.pm >> 5; }
;         else { src = src_ctx + (size_t)(u.pm - 128) * BM * 1024; dst = dst_ctx + (size_t)(u.pm - 128) * BM * 1024; b = 4; }
;         const float* g = gate + b * 6144;
;         const int col0 = u.pn * BM + wc * 32 + 4 * fq;
; #pragma unroll
;         for (int bj = 0; bj < 2; ++bj)
; #pragma unroll
;             for (int n = 0; n < 2; ++n) { const f32x4 gv = *(const f32x4*)(g + col0 + bj * HALF + n * 16);
; #pragma unroll
;                 for (int ai = 0; ai < 2; ++ai)
; #pragma unroll
;                     for (int m = 0; m < 4; ++m) { const size_t off = (size_t)(ai * HALF + wr * 64 + m * 16 + fr) * 1024 + col0 + bj * HALF + n * 16;
;                         const f32x4 s = *(const f32x4*)(src + off); *(f32x4*)(dst + off) = s + gv * acc[ai][bj][m][n]; } }
.LBB0_995:
	s_lshl_b64 s[10:11], s[16:17], 2
	s_add_u32 s10, s31, s10
	s_addc_u32 s11, s34, s11
	s_add_u32 s16, s14, 0x80000
	s_addc_u32 s17, s15, 0
	s_add_u32 s18, s12, 0x80000
	s_addc_u32 s19, s13, 0
	v_mbcnt_lo_u32_b32 v186, -1, 0
	v_mbcnt_hi_u32_b32 v186, -1, v186
	v_lshrrev_b32_e32 v187, 10, v142
	v_and_b32_e32 v187, 64, v187
	v_and_b32_e32 v188, 0x60, v169
	v_mul_u32_u24_e32 v189, 0xc0, v187
	v_mul_u32_u24_e32 v192, 0x60, v188
	v_add_u32_e32 v189, v189, v192
	v_add_u32_e32 v189, 0x20000, v189
	v_and_b32_e32 v192, 15, v186
	v_lshrrev_b32_e32 v193, 4, v186
	v_mul_u32_u24_e32 v192, 0x90, v192
	v_lshl_add_u32 v192, v193, 4, v192
	v_add_u32_e32 v38, v189, v192
	v_lshrrev_b32_e32 v190, 3, v186
	v_and_b32_e32 v191, 7, v186
	v_mul_u32_u24_e32 v192, 0x90, v190
	v_lshl_add_u32 v192, v191, 4, v192
	v_add_u32_e32 v250, v189, v192
	v_add_u32_e32 v193, v187, v190
	v_lshlrev_b32_e32 v193, 12, v193
	v_lshl_or_b32 v193, v188, 2, v193
	v_lshl_or_b32 v193, v191, 4, v193
	v_lshl_or_b32 v166, s40, 10, v193
	v_and_b32_e32 v251, 0xfff, v166
	v_add_u32_e32 v167, 0x8000, v166
	v_add_u32_e32 v180, 0x10000, v166
	v_add_u32_e32 v181, 0x18000, v166
	v_add_u32_e32 v202, 0x20000, v166
	v_add_u32_e32 v203, 0x28000, v166
	v_add_u32_e32 v212, 0x30000, v166
	v_add_u32_e32 v213, 0x38000, v166
	global_load_dwordx4 v[138:141], v251, s[10:11]
	global_load_dwordx4 v[162:165], v251, s[10:11] offset:512
	global_load_dwordx4 v[172:175], v166, s[14:15]
	global_load_dwordx4 v[176:179], v166, s[14:15] offset:512
	global_load_dwordx4 v[186:189], v167, s[14:15]
	global_load_dwordx4 v[190:193], v167, s[14:15] offset:512
	global_load_dwordx4 v[194:197], v180, s[14:15]
	global_load_dwordx4 v[198:201], v180, s[14:15] offset:512
	global_load_dwordx4 v[208:211], v181, s[14:15]
	global_load_dwordx4 v[218:221], v181, s[14:15] offset:512
	global_load_dwordx4 v[226:229], v202, s[14:15]
	global_load_dwordx4 v[230:233], v202, s[14:15] offset:512
	global_load_dwordx4 v[234:237], v203, s[14:15]
	global_load_dwordx4 v[238:241], v203, s[14:15] offset:512
	global_load_dwordx4 v[242:245], v212, s[14:15]
	global_load_dwordx4 v[246:249], v212, s[14:15] offset:512
	ds_write_b128 v38, v[134:137]
	ds_write_b128 v38, v[106:109] offset:64
	ds_read_b128 v[134:137], v250
	ds_read_b128 v[106:109], v250 offset:1152
	ds_write_b128 v38, v[82:85]
	ds_write_b128 v38, v[54:57] offset:64
	ds_read_b128 v[82:85], v250
	ds_read_b128 v[54:57], v250 offset:1152
	ds_write_b128 v38, v[130:133]
	ds_write_b128 v38, v[102:105] offset:64
	ds_read_b128 v[130:133], v250
	ds_read_b128 v[102:105], v250 offset:1152
	ds_write_b128 v38, v[74:77]
	ds_write_b128 v38, v[46:49] offset:64
	ds_read_b128 v[74:77], v250
	ds_read_b128 v[46:49], v250 offset:1152
	ds_write_b128 v38, v[126:129]
	ds_write_b128 v38, v[98:101] offset:64
	ds_read_b128 v[126:129], v250
	ds_read_b128 v[98:101], v250 offset:1152
	ds_write_b128 v38, v[66:69]
	ds_write_b128 v38, v[30:33] offset:64
	ds_read_b128 v[66:69], v250
	ds_read_b128 v[30:33], v250 offset:1152
	ds_write_b128 v38, v[122:125]
	ds_write_b128 v38, v[90:93] offset:64
	ds_read_b128 v[122:125], v250
	ds_read_b128 v[90:93], v250 offset:1152
	ds_write_b128 v38, v[58:61]
	ds_write_b128 v38, v[22:25] offset:64
	ds_read_b128 v[58:61], v250
	ds_read_b128 v[22:25], v250 offset:1152
	ds_write_b128 v38, v[118:121]
	ds_write_b128 v38, v[86:89] offset:64
	ds_read_b128 v[118:121], v250
	ds_read_b128 v[86:89], v250 offset:1152
	ds_write_b128 v38, v[50:53]
	ds_write_b128 v38, v[14:17] offset:64
	ds_read_b128 v[50:53], v250
	ds_read_b128 v[14:17], v250 offset:1152
	ds_write_b128 v38, v[114:117]
	ds_write_b128 v38, v[78:81] offset:64
	ds_read_b128 v[114:117], v250
	ds_read_b128 v[78:81], v250 offset:1152
	ds_write_b128 v38, v[42:45]
	ds_write_b128 v38, v[10:13] offset:64
	ds_read_b128 v[42:45], v250
	ds_read_b128 v[10:13], v250 offset:1152
	ds_write_b128 v38, v[110:113]
	ds_write_b128 v38, v[70:73] offset:64
	ds_read_b128 v[110:113], v250
	ds_read_b128 v[70:73], v250 offset:1152
	ds_write_b128 v38, v[26:29]
	ds_write_b128 v38, v[6:9] offset:64
	ds_read_b128 v[26:29], v250
	ds_read_b128 v[6:9], v250 offset:1152
	ds_write_b128 v38, v[94:97]
	ds_write_b128 v38, v[62:65] offset:64
	ds_read_b128 v[94:97], v250
	ds_read_b128 v[62:65], v250 offset:1152
	ds_write_b128 v38, v[18:21]
	ds_write_b128 v38, v[2:5] offset:64
	ds_read_b128 v[18:21], v250
	ds_read_b128 v[2:5], v250 offset:1152
	s_waitcnt lgkmcnt(0)
	s_waitcnt vmcnt(13)
	v_pk_fma_f32 v[134:135], v[134:135], v[138:139], v[172:173]
	v_pk_fma_f32 v[136:137], v[136:137], v[140:141], v[174:175]
	global_store_dwordx4 v166, v[134:137], s[12:13] sc1
	global_load_dwordx4 v[172:175], v213, s[14:15]
	s_waitcnt vmcnt(14)
	v_pk_fma_f32 v[82:83], v[82:83], v[162:163], v[176:177]
	v_pk_fma_f32 v[84:85], v[84:85], v[164:165], v[178:179]
	global_store_dwordx4 v166, v[82:85], s[12:13] offset:512 sc1
	global_load_dwordx4 v[176:179], v213, s[14:15] offset:512
	s_waitcnt vmcnt(15)
	v_pk_fma_f32 v[106:107], v[106:107], v[138:139], v[186:187]
	v_pk_fma_f32 v[108:109], v[108:109], v[140:141], v[188:189]
	global_store_dwordx4 v167, v[106:109], s[12:13] sc1
	global_load_dwordx4 v[186:189], v166, s[16:17]
	s_waitcnt vmcnt(16)
	v_pk_fma_f32 v[54:55], v[54:55], v[162:163], v[190:191]
	v_pk_fma_f32 v[56:57], v[56:57], v[164:165], v[192:193]
	global_store_dwordx4 v167, v[54:57], s[12:13] offset:512 sc1
	global_load_dwordx4 v[190:193], v166, s[16:17] offset:512
	s_waitcnt vmcnt(17)
	v_pk_fma_f32 v[130:131], v[130:131], v[138:139], v[194:195]
	v_pk_fma_f32 v[132:133], v[132:133], v[140:141], v[196:197]
	global_store_dwordx4 v180, v[130:133], s[12:13] sc1
	global_load_dwordx4 v[194:197], v167, s[16:17]
	s_waitcnt vmcnt(18)
; #define PG8_BAR __builtin_amdgcn_s_barrier()
;     __device__ __forceinline__ void operator()(const f32x4 (&acc)[2][2][4][2], const Unit& u, int wr, int wc, int fr, int fq) const {
;     ...
;             for (int n = 0; n < 2; ++n) { const f32x4 gv = *(const f32x4*)(g + col0 + bj * HALF + n * 16);
; #pragma unroll
;                 for (int ai = 0; ai < 2; ++ai)
; #pragma unroll
;                     for (int m = 0; m < 4; ++m) { const size_t off = (size_t)(ai * HALF + wr * 64 + m * 16 + fr) * 1024 + col0 + bj * HALF + n * 16;
;                         const f32x4 s = *(const f32x4*)(src + off); *(f32x4*)(dst + off) = s + gv * acc[ai][bj][m][n]; } }
; template <class Epi, class Sched, bool ALIGN_EPI = false, bool SP2 = false>
; __device__ __forceinline__ void gemm_phase(PG8_LAS unsigned char* lds, const Gemm g, const Sched& S, const Epi& E) {
;     ...
;         if (!has_next) break;
; #pragma unroll
;         for (int a = 0; a < 2; ++a)
; #pragma unroll
;             for (int b = 0; b < 2; ++b)
; #pragma unroll
;                 for (int m = 0; m < 4; ++m)
; #pragma unroll
;                     for (int n = 0; n < 2; ++n) acc[a][b][m][n] = (f32x4){0.f, 0.f, 0.f, 0.f};
;         cur = nxt; cA = nA; cB = nB; ++ui;
;         if constexpr (ALIGN_EPI) { if (wr == 1) PG8_BAR; }
	v_pk_fma_f32 v[74:75], v[74:75], v[162:163], v[198:199]
	v_pk_fma_f32 v[76:77], v[76:77], v[164:165], v[200:201]
	global_store_dwordx4 v180, v[74:77], s[12:13] offset:512 sc1
	global_load_dwordx4 v[198:201], v167, s[16:17] offset:512
	s_waitcnt vmcnt(19)
	v_pk_fma_f32 v[102:103], v[102:103], v[138:139], v[208:209]
	v_pk_fma_f32 v[104:105], v[104:105], v[140:141], v[210:211]
	global_store_dwordx4 v181, v[102:105], s[12:13] sc1
	global_load_dwordx4 v[208:211], v180, s[16:17]
	s_waitcnt vmcnt(20)
	v_pk_fma_f32 v[46:47], v[46:47], v[162:163], v[218:219]
	v_pk_fma_f32 v[48:49], v[48:49], v[164:165], v[220:221]
	global_store_dwordx4 v181, v[46:49], s[12:13] offset:512 sc1
	global_load_dwordx4 v[218:221], v180, s[16:17] offset:512
	s_waitcnt vmcnt(21)
	v_pk_fma_f32 v[126:127], v[126:127], v[138:139], v[226:227]
	v_pk_fma_f32 v[128:129], v[128:129], v[140:141], v[228:229]
	global_store_dwordx4 v202, v[126:129], s[12:13] sc1
	global_load_dwordx4 v[226:229], v181, s[16:17]
	s_waitcnt vmcnt(22)
	v_pk_fma_f32 v[66:67], v[66:67], v[162:163], v[230:231]
	v_pk_fma_f32 v[68:69], v[68:69], v[164:165], v[232:233]
	global_store_dwordx4 v202, v[66:69], s[12:13] offset:512 sc1
	global_load_dwordx4 v[230:233], v181, s[16:17] offset:512
	s_waitcnt vmcnt(23)
	v_pk_fma_f32 v[98:99], v[98:99], v[138:139], v[234:235]
	v_pk_fma_f32 v[100:101], v[100:101], v[140:141], v[236:237]
	global_store_dwordx4 v203, v[98:101], s[12:13] sc1
	global_load_dwordx4 v[234:237], v202, s[16:17]
	s_waitcnt vmcnt(24)
	v_pk_fma_f32 v[30:31], v[30:31], v[162:163], v[238:239]
	v_pk_fma_f32 v[32:33], v[32:33], v[164:165], v[240:241]
	global_store_dwordx4 v203, v[30:33], s[12:13] offset:512 sc1
	global_load_dwordx4 v[238:241], v202, s[16:17] offset:512
	s_waitcnt vmcnt(25)
	v_pk_fma_f32 v[122:123], v[122:123], v[138:139], v[242:243]
	v_pk_fma_f32 v[124:125], v[124:125], v[140:141], v[244:245]
	global_store_dwordx4 v212, v[122:125], s[12:13] sc1
	global_load_dwordx4 v[242:245], v203, s[16:17]
	s_waitcnt vmcnt(26)
	v_pk_fma_f32 v[58:59], v[58:59], v[162:163], v[246:247]
	v_pk_fma_f32 v[60:61], v[60:61], v[164:165], v[248:249]
	global_store_dwordx4 v212, v[58:61], s[12:13] offset:512 sc1
	global_load_dwordx4 v[246:249], v203, s[16:17] offset:512
	s_waitcnt vmcnt(26)
	v_pk_fma_f32 v[90:91], v[90:91], v[138:139], v[172:173]
	v_pk_fma_f32 v[92:93], v[92:93], v[140:141], v[174:175]
	global_store_dwordx4 v213, v[90:93], s[12:13] sc1
	global_load_dwordx4 v[172:175], v212, s[16:17]
	s_waitcnt vmcnt(26)
	v_pk_fma_f32 v[22:23], v[22:23], v[162:163], v[176:177]
	v_pk_fma_f32 v[24:25], v[24:25], v[164:165], v[178:179]
	global_store_dwordx4 v213, v[22:25], s[12:13] offset:512 sc1
	global_load_dwordx4 v[176:179], v212, s[16:17] offset:512
	s_waitcnt vmcnt(26)
	v_pk_fma_f32 v[118:119], v[118:119], v[138:139], v[186:187]
	v_pk_fma_f32 v[120:121], v[120:121], v[140:141], v[188:189]
	global_store_dwordx4 v166, v[118:121], s[18:19] sc1
	global_load_dwordx4 v[186:189], v213, s[16:17]
	s_waitcnt vmcnt(26)
	v_pk_fma_f32 v[50:51], v[50:51], v[162:163], v[190:191]
	v_pk_fma_f32 v[52:53], v[52:53], v[164:165], v[192:193]
	global_store_dwordx4 v166, v[50:53], s[18:19] offset:512 sc1
	global_load_dwordx4 v[190:193], v213, s[16:17] offset:512
	s_waitcnt vmcnt(26)
	v_pk_fma_f32 v[86:87], v[86:87], v[138:139], v[194:195]
	v_pk_fma_f32 v[88:89], v[88:89], v[140:141], v[196:197]
	global_store_dwordx4 v167, v[86:89], s[18:19] sc1
	s_waitcnt vmcnt(25)
	v_pk_fma_f32 v[14:15], v[14:15], v[162:163], v[198:199]
	v_pk_fma_f32 v[16:17], v[16:17], v[164:165], v[200:201]
	global_store_dwordx4 v167, v[14:17], s[18:19] offset:512 sc1
	s_waitcnt vmcnt(24)
	v_pk_fma_f32 v[114:115], v[114:115], v[138:139], v[208:209]
	v_pk_fma_f32 v[116:117], v[116:117], v[140:141], v[210:211]
	global_store_dwordx4 v180, v[114:117], s[18:19] sc1
	s_waitcnt vmcnt(23)
	v_pk_fma_f32 v[42:43], v[42:43], v[162:163], v[218:219]
	v_pk_fma_f32 v[44:45], v[44:45], v[164:165], v[220:221]
	global_store_dwordx4 v180, v[42:45], s[18:19] offset:512 sc1
	s_waitcnt vmcnt(22)
	v_pk_fma_f32 v[78:79], v[78:79], v[138:139], v[226:227]
	v_pk_fma_f32 v[80:81], v[80:81], v[140:141], v[228:229]
	global_store_dwordx4 v181, v[78:81], s[18:19] sc1
	s_waitcnt vmcnt(21)
	v_pk_fma_f32 v[10:11], v[10:11], v[162:163], v[230:231]
	v_pk_fma_f32 v[12:13], v[12:13], v[164:165], v[232:233]
	global_store_dwordx4 v181, v[10:13], s[18:19] offset:512 sc1
	s_waitcnt vmcnt(20)
	v_pk_fma_f32 v[110:111], v[110:111], v[138:139], v[234:235]
	v_pk_fma_f32 v[112:113], v[112:113], v[140:141], v[236:237]
	global_store_dwordx4 v202, v[110:113], s[18:19] sc1
	s_waitcnt vmcnt(19)
	v_pk_fma_f32 v[26:27], v[26:27], v[162:163], v[238:239]
	v_pk_fma_f32 v[28:29], v[28:29], v[164:165], v[240:241]
	global_store_dwordx4 v202, v[26:29], s[18:19] offset:512 sc1
	s_waitcnt vmcnt(18)
	v_pk_fma_f32 v[70:71], v[70:71], v[138:139], v[242:243]
	v_pk_fma_f32 v[72:73], v[72:73], v[140:141], v[244:245]
	global_store_dwordx4 v203, v[70:73], s[18:19] sc1
	s_waitcnt vmcnt(17)
	v_pk_fma_f32 v[6:7], v[6:7], v[162:163], v[246:247]
	v_pk_fma_f32 v[8:9], v[8:9], v[164:165], v[248:249]
	global_store_dwordx4 v203, v[6:9], s[18:19] offset:512 sc1
	s_waitcnt vmcnt(16)
	v_pk_fma_f32 v[94:95], v[94:95], v[138:139], v[172:173]
	v_pk_fma_f32 v[96:97], v[96:97], v[140:141], v[174:175]
	global_store_dwordx4 v212, v[94:97], s[18:19] sc1
	s_waitcnt vmcnt(15)
	v_pk_fma_f32 v[18:19], v[18:19], v[162:163], v[176:177]
	v_pk_fma_f32 v[20:21], v[20:21], v[164:165], v[178:179]
	global_store_dwordx4 v212, v[18:21], s[18:19] offset:512 sc1
	s_waitcnt vmcnt(14)
	v_pk_fma_f32 v[62:63], v[62:63], v[138:139], v[186:187]
	v_pk_fma_f32 v[64:65], v[64:65], v[140:141], v[188:189]
	global_store_dwordx4 v213, v[62:65], s[18:19] sc1
	s_waitcnt vmcnt(13)
	v_pk_fma_f32 v[2:3], v[2:3], v[162:163], v[190:191]
	v_pk_fma_f32 v[4:5], v[4:5], v[164:165], v[192:193]
	global_store_dwordx4 v213, v[2:5], s[18:19] offset:512 sc1
	s_mov_b64 s[10:11], -1
	s_and_b64 vcc, exec, s[4:5]
	s_cbranch_vccnz .LBB0_978
	s_andn2_b64 vcc, exec, s[2:3]
	s_cbranch_vccnz .LBB0_977
	s_barrier
	s_branch .LBB0_977
